# indexer scoring loop: scalar v_mul/v_fmac weighted sums instead of packed v_pk_mul/v_pk_fma beside the MFMAs
# speedup vs baseline: 1.0039x; 1.0039x over previous
; #define IDX_TOT(j) ({ const f32x4 w4 = wreg[rb * 4 + (j)]; \
;                 const float part = w4[0] * reluf(c[4 * (j)]) + w4[1] * reluf(c[4 * (j) + 1]) + w4[2] * reluf(c[4 * (j) + 2]) + w4[3] * reluf(c[4 * (j) + 3]); swap32_add(part); })
; __device__ __forceinline__ void idx_unit(unsigned char* lds, const bf16_t* P, int b, int qb16, unsigned* bits) {
;     ...
;         for (int rb = 0; rb < 4; ++rb) {
;             f32x16 c;
; #pragma unroll
;             for (int r = 0; r < 16; ++r) c[r] = 0.f;
; #pragma unroll
;             for (int kk = 0; kk < 4; ++kk) c = __builtin_amdgcn_mfma_f32_32x32x16_bf16(aq[rb][kk], bk[kk], c, 0, 0, 0);
;             asm volatile("s_nop 15\n\ts_nop 7" : "+v"(c));
;             float tq0, tq1, tq2, tq3;
;     ...
;             tq0 = IDX_TOT(0); tq1 = IDX_TOT(1); tq2 = IDX_TOT(2); tq3 = IDX_TOT(3);
;     ...
;             const float ts0 = hi ? tq2 : tq0, ts1 = hi ? tq3 : tq1;
; #pragma unroll
;             for (int jj = 0; jj < 2; ++jj) { const float tv = jj ? ts1 : ts0; const int q = rb * 4 + 2 * hi + jj;
;                 unsigned short kv = 0;
;                 if (key <= t0 + q) { const _Float16 hv = (_Float16)tv; const unsigned short hb = __builtin_bit_cast(unsigned short, hv); kv = (hb & 0x8000u) ? (unsigned short)~hb : (unsigned short)(hb | 0x8000u); }
;                 sc[q * 4096 + key] = kv; }
.Lidx_go:
	s_waitcnt lgkmcnt(0)
	v_mfma_f32_32x32x16_bf16 v[198:213], v[42:45], v[174:177], 0
	v_max_f32_e32 v2, 0, v2
	v_max_f32_e32 v3, 0, v3
	v_max_f32_e32 v4, 0, v4
	v_max_f32_e32 v5, 0, v5
	v_max_f32_e32 v6, 0, v6
	v_max_f32_e32 v7, 0, v7
	v_max_f32_e32 v8, 0, v8
	v_max_f32_e32 v9, 0, v9
	v_mfma_f32_32x32x16_bf16 v[198:213], v[34:37], v[170:173], v[198:213]
	v_max_f32_e32 v10, 0, v10
	v_max_f32_e32 v11, 0, v11
	v_max_f32_e32 v12, 0, v12
	v_max_f32_e32 v13, 0, v13
	v_max_f32_e32 v14, 0, v14
	v_max_f32_e32 v15, 0, v15
	v_max_f32_e32 v16, 0, v16
	v_max_f32_e32 v17, 0, v17
	v_mfma_f32_32x32x16_bf16 v[198:213], v[38:41], v[166:169], v[198:213]
	v_mul_f32_e32 v3, v139, v3
	v_mul_f32_e32 v7, v143, v7
	v_mul_f32_e32 v11, v135, v11
	v_mul_f32_e32 v15, v131, v15
	v_fmac_f32_e32 v3, v138, v2
	v_fmac_f32_e32 v7, v142, v6
	v_fmac_f32_e32 v11, v134, v10
	v_fmac_f32_e32 v15, v130, v14
	v_mfma_f32_32x32x16_bf16 v[198:213], v[46:49], v[162:165], v[198:213]
	v_fmac_f32_e32 v3, v140, v4
	v_fmac_f32_e32 v7, v144, v8
	v_fmac_f32_e32 v11, v136, v12
	v_fmac_f32_e32 v15, v132, v16
	v_fmac_f32_e32 v3, v141, v5
	v_fmac_f32_e32 v7, v145, v9
	v_fmac_f32_e32 v11, v137, v13
	v_fmac_f32_e32 v15, v133, v17
	s_nop 0
	v_permlane32_swap_b32_e32 v3, v11
	s_nop 0
	v_permlane32_swap_b32_e32 v7, v15
	v_add_f32_e32 v3, v3, v11
	v_add_f32_e32 v7, v7, v15
	v_cvt_f16_f32_e32 v3, v3
	v_cvt_f16_f32_e32 v7, v7
	v_bfe_i32 v2, v3, 15, 1
	v_bfe_i32 v6, v7, 15, 1
	v_bitop3_b32 v3, v3, v2, s101 bitop3:0x1e
	v_bitop3_b32 v7, v7, v6, s101 bitop3:0x1e
	v_cmp_le_i32_e32 vcc, v180, v183
	v_cmp_le_i32_e64 s[6:7], v180, v184
	s_nop 0
	v_cndmask_b32_e32 v3, 0, v3, vcc
	v_cndmask_b32_e64 v7, 0, v7, s[6:7]
	ds_write_b16 v197, v3
	ds_write_b16 v197, v7 offset:8192
	v_mfma_f32_32x32x16_bf16 v[2:17], v[58:61], v[174:177], 0
	v_max_f32_e32 v198, 0, v198
	v_max_f32_e32 v199, 0, v199
	v_max_f32_e32 v200, 0, v200
	v_max_f32_e32 v201, 0, v201
	v_max_f32_e32 v202, 0, v202
	v_max_f32_e32 v203, 0, v203
	v_max_f32_e32 v204, 0, v204
	v_max_f32_e32 v205, 0, v205
	v_mfma_f32_32x32x16_bf16 v[2:17], v[50:53], v[170:173], v[2:17]
	v_max_f32_e32 v206, 0, v206
	v_max_f32_e32 v207, 0, v207
	v_max_f32_e32 v208, 0, v208
	v_max_f32_e32 v209, 0, v209
	v_max_f32_e32 v210, 0, v210
	v_max_f32_e32 v211, 0, v211
	v_max_f32_e32 v212, 0, v212
	v_max_f32_e32 v213, 0, v213
	v_mfma_f32_32x32x16_bf16 v[2:17], v[54:57], v[166:169], v[2:17]
	v_mul_f32_e32 v199, v127, v199
	v_mul_f32_e32 v203, v123, v203
	v_mul_f32_e32 v207, v119, v207
	v_mul_f32_e32 v211, v115, v211
	v_fmac_f32_e32 v199, v126, v198
	v_fmac_f32_e32 v203, v122, v202
	v_fmac_f32_e32 v207, v118, v206
	v_fmac_f32_e32 v211, v114, v210
	v_mfma_f32_32x32x16_bf16 v[2:17], v[62:65], v[162:165], v[2:17]
	v_fmac_f32_e32 v199, v128, v200
	v_fmac_f32_e32 v203, v124, v204
	v_fmac_f32_e32 v207, v120, v208
	v_fmac_f32_e32 v211, v116, v212
	v_fmac_f32_e32 v199, v129, v201
	v_fmac_f32_e32 v203, v125, v205
	v_fmac_f32_e32 v207, v121, v209
	v_fmac_f32_e32 v211, v117, v213
	s_nop 0
	v_permlane32_swap_b32_e32 v199, v207
	s_nop 0
	v_permlane32_swap_b32_e32 v203, v211
	v_add_f32_e32 v199, v199, v207
	v_add_f32_e32 v203, v203, v211
	v_cvt_f16_f32_e32 v199, v199
	v_cvt_f16_f32_e32 v203, v203
	v_bfe_i32 v198, v199, 15, 1
	v_bfe_i32 v202, v203, 15, 1
	v_bitop3_b32 v199, v199, v198, s101 bitop3:0x1e
	v_bitop3_b32 v203, v203, v202, s101 bitop3:0x1e
	v_cmp_le_i32_e32 vcc, v180, v185
	v_cmp_le_i32_e64 s[6:7], v180, v187
	s_nop 0
	v_cndmask_b32_e32 v199, 0, v199, vcc
	v_cndmask_b32_e64 v203, 0, v203, s[6:7]
	ds_write_b16 v197, v199 offset:32768
	ds_write_b16 v197, v203 offset:40960
	v_mfma_f32_32x32x16_bf16 v[198:213], v[74:77], v[174:177], 0
	v_max_f32_e32 v2, 0, v2
	v_max_f32_e32 v3, 0, v3
	v_max_f32_e32 v4, 0, v4
	v_max_f32_e32 v5, 0, v5
	v_max_f32_e32 v6, 0, v6
	v_max_f32_e32 v7, 0, v7
	v_max_f32_e32 v8, 0, v8
	v_max_f32_e32 v9, 0, v9
	v_mfma_f32_32x32x16_bf16 v[198:213], v[66:69], v[170:173], v[198:213]
	v_max_f32_e32 v10, 0, v10
	v_max_f32_e32 v11, 0, v11
	v_max_f32_e32 v12, 0, v12
	v_max_f32_e32 v13, 0, v13
	v_max_f32_e32 v14, 0, v14
	v_max_f32_e32 v15, 0, v15
	v_max_f32_e32 v16, 0, v16
	v_max_f32_e32 v17, 0, v17
	v_mfma_f32_32x32x16_bf16 v[198:213], v[70:73], v[166:169], v[198:213]
	v_mul_f32_e32 v3, v111, v3
	v_mul_f32_e32 v7, v107, v7
	v_mul_f32_e32 v11, v103, v11
	v_mul_f32_e32 v15, v99, v15
	v_fmac_f32_e32 v3, v110, v2
	v_fmac_f32_e32 v7, v106, v6
	v_fmac_f32_e32 v11, v102, v10
	v_fmac_f32_e32 v15, v98, v14
	v_mfma_f32_32x32x16_bf16 v[198:213], v[78:81], v[162:165], v[198:213]
	v_fmac_f32_e32 v3, v112, v4
	v_fmac_f32_e32 v7, v108, v8
	v_fmac_f32_e32 v11, v104, v12
	v_fmac_f32_e32 v15, v100, v16
	v_fmac_f32_e32 v3, v113, v5
	v_fmac_f32_e32 v7, v109, v9
	v_fmac_f32_e32 v11, v105, v13
	v_fmac_f32_e32 v15, v101, v17
	s_nop 0
	v_permlane32_swap_b32_e32 v3, v11
	s_nop 0
	v_permlane32_swap_b32_e32 v7, v15
	v_add_f32_e32 v3, v3, v11
	v_add_f32_e32 v7, v7, v15
	v_cvt_f16_f32_e32 v3, v3
	v_cvt_f16_f32_e32 v7, v7
	v_bfe_i32 v2, v3, 15, 1
	v_bfe_i32 v6, v7, 15, 1
	v_bitop3_b32 v3, v3, v2, s101 bitop3:0x1e
	v_bitop3_b32 v7, v7, v6, s101 bitop3:0x1e
	v_cmp_le_i32_e32 vcc, v180, v192
	v_cmp_le_i32_e64 s[6:7], v180, v193
	s_nop 0
	v_cndmask_b32_e32 v3, 0, v3, vcc
	v_cndmask_b32_e64 v7, 0, v7, s[6:7]
	ds_write_b16 v196, v3
	ds_write_b16 v196, v7 offset:8192
	s_waitcnt vmcnt(0)
; #define IDX_TOT(j) ({ const f32x4 w4 = wreg[rb * 4 + (j)]; \
;                 const float part = w4[0] * reluf(c[4 * (j)]) + w4[1] * reluf(c[4 * (j) + 1]) + w4[2] * reluf(c[4 * (j) + 2]) + w4[3] * reluf(c[4 * (j) + 3]); swap32_add(part); })
; __device__ __forceinline__ void idx_unit(unsigned char* lds, const bf16_t* P, int b, int qb16, unsigned* bits) {
;     ...
;         for (int rb = 0; rb < 4; ++rb) {
;             f32x16 c;
; #pragma unroll
;             for (int r = 0; r < 16; ++r) c[r] = 0.f;
; #pragma unroll
;             for (int kk = 0; kk < 4; ++kk) c = __builtin_amdgcn_mfma_f32_32x32x16_bf16(aq[rb][kk], bk[kk], c, 0, 0, 0);
;             asm volatile("s_nop 15\n\ts_nop 7" : "+v"(c));
;             float tq0, tq1, tq2, tq3;
;     ...
;             tq0 = IDX_TOT(0); tq1 = IDX_TOT(1); tq2 = IDX_TOT(2); tq3 = IDX_TOT(3);
;     ...
;             const float ts0 = hi ? tq2 : tq0, ts1 = hi ? tq3 : tq1;
; #pragma unroll
;             for (int jj = 0; jj < 2; ++jj) { const float tv = jj ? ts1 : ts0; const int q = rb * 4 + 2 * hi + jj;
;                 unsigned short kv = 0;
;                 if (key <= t0 + q) { const _Float16 hv = (_Float16)tv; const unsigned short hb = __builtin_bit_cast(unsigned short, hv); kv = (hb & 0x8000u) ? (unsigned short)~hb : (unsigned short)(hb | 0x8000u); }
;                 sc[q * 4096 + key] = kv; }
;         }
; #pragma unroll
;         for (int kk = 0; kk < 4; ++kk) bk[kk] = bn[kk];
	v_mov_b64_e32 v[162:163], v[154:155]
	v_mov_b64_e32 v[164:165], v[156:157]
	v_mov_b64_e32 v[166:167], v[146:147]
	v_mov_b64_e32 v[168:169], v[148:149]
	v_mov_b64_e32 v[170:171], v[150:151]
	v_mov_b64_e32 v[172:173], v[152:153]
	v_mov_b64_e32 v[174:175], v[158:159]
	v_mov_b64_e32 v[176:177], v[160:161]
	s_nop 1
	v_mfma_f32_32x32x16_bf16 v[2:17], v[26:29], v[174:177], 0
	v_max_f32_e32 v198, 0, v198
	v_max_f32_e32 v199, 0, v199
	v_max_f32_e32 v200, 0, v200
	v_max_f32_e32 v201, 0, v201
	v_max_f32_e32 v202, 0, v202
	v_max_f32_e32 v203, 0, v203
	v_max_f32_e32 v204, 0, v204
	v_max_f32_e32 v205, 0, v205
	v_mfma_f32_32x32x16_bf16 v[2:17], v[18:21], v[170:173], v[2:17]
	v_max_f32_e32 v206, 0, v206
	v_max_f32_e32 v207, 0, v207
	v_max_f32_e32 v208, 0, v208
	v_max_f32_e32 v209, 0, v209
	v_max_f32_e32 v210, 0, v210
	v_max_f32_e32 v211, 0, v211
	v_max_f32_e32 v212, 0, v212
	v_max_f32_e32 v213, 0, v213
	v_mfma_f32_32x32x16_bf16 v[2:17], v[22:25], v[166:169], v[2:17]
	v_mul_f32_e32 v199, v95, v199
	v_mul_f32_e32 v203, v91, v203
	v_mul_f32_e32 v207, v87, v207
	v_mul_f32_e32 v211, v83, v211
	v_fmac_f32_e32 v199, v94, v198
	v_fmac_f32_e32 v203, v90, v202
	v_fmac_f32_e32 v207, v86, v206
	v_fmac_f32_e32 v211, v82, v210
	v_mfma_f32_32x32x16_bf16 v[2:17], v[30:33], v[162:165], v[2:17]
	v_fmac_f32_e32 v199, v96, v200
	v_fmac_f32_e32 v203, v92, v204
	v_fmac_f32_e32 v207, v88, v208
	v_fmac_f32_e32 v211, v84, v212
	v_fmac_f32_e32 v199, v97, v201
	v_fmac_f32_e32 v203, v93, v205
	v_fmac_f32_e32 v207, v89, v209
	v_fmac_f32_e32 v211, v85, v213
	s_nop 0
	v_permlane32_swap_b32_e32 v199, v207
	s_nop 0
	v_permlane32_swap_b32_e32 v203, v211
	v_add_f32_e32 v199, v199, v207
	v_add_f32_e32 v203, v203, v211
	v_cvt_f16_f32_e32 v199, v199
	v_cvt_f16_f32_e32 v203, v203
	v_bfe_i32 v198, v199, 15, 1
	v_bfe_i32 v202, v203, 15, 1
	v_bitop3_b32 v199, v199, v198, s101 bitop3:0x1e
	v_bitop3_b32 v203, v203, v202, s101 bitop3:0x1e
	v_cmp_le_i32_e32 vcc, v180, v194
	v_cmp_le_i32_e64 s[6:7], v180, v195
	s_nop 0
	v_cndmask_b32_e32 v199, 0, v199, vcc
	v_cndmask_b32_e64 v203, 0, v203, s[6:7]
	ds_write_b16 v196, v199 offset:32768
	ds_write_b16 v196, v203 offset:40960
	v_add_u32_e32 v180, 0x100, v180
	v_add_u32_e32 v196, 0x200, v196
	v_add_u32_e32 v197, 0x200, v197
	s_and_b64 vcc, exec, s[0:1]
	s_cbranch_vccz .LBB0_399
